# combine loop: the three mid-iteration loads (two bf16 rows + gain vector) issued with the first batch into v90-v97, vmcnt waits regenerated (on v62)
# baseline (speedup 1.0000x reference)
; DI void phase_combine(CParams& p, int layer, const float* __restrict__ xg) {
;     ...
;   for (int r = blockIdx.x * 4 + wave; r < TG; r += gridDim.x * 4) {
;     {
;       float lg[3];
; #pragma unroll
;       for (int g = 0; g < 3; ++g) lg[g] = LSE[((size_t)g * TG + r) * 4 + head];
;       const float mx = fmaxf(lg[0], fmaxf(lg[1], lg[2]));
;       float wg[3], den = 0.f;
; #pragma unroll
;       for (int g = 0; g < 3; ++g) { wg[g] = exp2_(lg[g] - mx); den += wg[g]; }
;       const float id = 1.f / den;
;       float o[4] = {0.f, 0.f, 0.f, 0.f};
; #pragma unroll
;       for (int g = 0; g < 3; ++g) {
;         const u32x2 u = ((const u32x2*)(OD + ((size_t)g * TG + r) * 256))[lane];
;         const float c = wg[g] * id;
;         o[0] += c * __uint_as_float(u.x << 16); o[1] += c * __uint_as_float(u.x & 0xffff0000u);
;         o[2] += c * __uint_as_float(u.y << 16); o[3] += c * __uint_as_float(u.y & 0xffff0000u);
;       }
;       u32x2 ou; ou.x = pack2(o[0], o[1]); ou.y = pack2(o[2], o[3]);
;       ((u32x2*)(Y + (size_t)r * 1024 + 768))[lane] = ou;
;     }
;     {
;       const u32x2 uf = ((const u32x2*)(OFb + (size_t)r * 256))[lane];
;       const u32x2 ub = ((const u32x2*)(OBb + (size_t)r * 256))[lane];
;       const u32x2 uz = ((const u32x2*)(PR + (size_t)r * NPR + C_Z))[lane];
;       float o[4], z[4];
;       o[0] = __uint_as_float(uf.x << 16) + __uint_as_float(ub.x << 16);
;       o[1] = __uint_as_float(uf.x & 0xffff0000u) + __uint_as_float(ub.x & 0xffff0000u);
;       o[2] = __uint_as_float(uf.y << 16) + __uint_as_float(ub.y << 16);
;       o[3] = __uint_as_float(uf.y & 0xffff0000u) + __uint_as_float(ub.y & 0xffff0000u);
;       z[0] = __uint_as_float(uz.x << 16); z[1] = __uint_as_float(uz.x & 0xffff0000u);
;       z[2] = __uint_as_float(uz.y << 16); z[3] = __uint_as_float(uz.y & 0xffff0000u);
;       float ss = o[0] * o[0] + o[1] * o[1] + o[2] * o[2] + o[3] * o[3];
;       ss += __shfl_xor(ss, 1); ss += __shfl_xor(ss, 2); ss += __shfl_xor(ss, 4); ss += __shfl_xor(ss, 8);
;       const float rs = rsqrtf(ss * (1.f / 64.f) + EPS);
;       const float4 gg = ((const float4*)gdn)[lane & 15];
;       u32x2 ou;
;       ou.x = pack2(o[0] * rs * gg.x * siluf_(z[0]), o[1] * rs * gg.y * siluf_(z[1]));
;       ou.y = pack2(o[2] * rs * gg.z * siluf_(z[2]), o[3] * rs * gg.w * siluf_(z[3]));
;       ((u32x2*)(Y + (size_t)r * 1024 + 512))[lane] = ou;
;     }
;     {
.LBB0_907:
	v_ashrrev_i32_e32 v19, 31, v18
	v_lshlrev_b64 v[42:43], 9, v[18:19]
	v_lshl_add_u64 v[8:9], v[22:23], 0, v[42:43]
	s_mov_b32 s8, 0x1000000
	v_lshl_add_u64 v[2:3], v[18:19], 4, v[20:21]
	v_add_co_u32_e64 v10, s[44:45], s8, v8
	v_add_co_u32_e32 v4, vcc, 0x80000, v2
	s_nop 0
	v_addc_co_u32_e64 v11, s[44:45], 0, v9, s[44:45]
	s_brev_b32 s8, 64
	v_addc_co_u32_e32 v5, vcc, 0, v3, vcc
	global_load_dwordx2 v[52:53], v[10:11], off
	v_add_co_u32_e64 v10, s[44:45], s8, v8
	v_add_co_u32_e32 v6, vcc, 0x100000, v2
	s_nop 0
	v_addc_co_u32_e64 v11, s[44:45], 0, v9, s[44:45]
	global_load_dwordx2 v[54:55], v[10:11], off
	v_addc_co_u32_e32 v7, vcc, 0, v3, vcc
	global_load_dword v66, v[2:3], off
	global_load_dword v67, v[4:5], off
	global_load_dword v68, v[6:7], off
	global_load_dwordx2 v[56:57], v[8:9], off
	v_lshlrev_b64 v[38:39], 11, v[18:19]
	v_lshlrev_b64 v[4:5], 12, v[18:19]
	v_mov_b64_e32 v[2:3], s[46:47]
	v_mad_i64_i32 v[2:3], s[8:9], v18, s16, v[2:3]
	v_lshl_add_u64 v[2:3], v[2:3], 0, v[0:1]
	s_brev_b32 s8, 16
	v_add_co_u32_e32 v58, vcc, s8, v2
	v_lshl_add_u64 v[4:5], v[34:35], 0, v[4:5]
	s_nop 0
	v_addc_co_u32_e32 v59, vcc, 0, v3, vcc
	global_load_dwordx4 v[14:17], v[4:5], off
	global_load_dwordx4 v[6:9], v[4:5], off offset:1024
	global_load_dwordx4 v[10:13], v[4:5], off offset:2048
	s_nop 0
	global_load_dwordx4 v[2:5], v[4:5], off offset:3072
	s_nop 0
	global_load_dwordx2 v[58:59], v[58:59], off offset:3840
	v_lshl_add_u64 v[40:41], v[32:33], 0, v[38:39]
	v_lshl_add_u64 v[44:45], v[24:25], 0, v[42:43]
	v_lshl_add_u64 v[42:43], v[26:27], 0, v[42:43]
	v_lshl_add_u64 v[38:39], v[36:37], 0, v[38:39]
	global_load_dwordx2 v[90:91], v[44:45], off
	global_load_dwordx2 v[92:93], v[42:43], off
	global_load_dwordx4 v[94:97], v[28:29], off
	v_add_u32_e32 v18, s56, v18
	s_waitcnt vmcnt(13)
	v_lshlrev_b32_e32 v60, 16, v52
	v_and_b32_e32 v61, 0xffff0000, v52
	v_lshlrev_b32_e32 v52, 16, v53
	v_and_b32_e32 v53, 0xffff0000, v53
	s_waitcnt vmcnt(12)
	v_lshlrev_b32_e32 v62, 16, v54
	v_and_b32_e32 v63, 0xffff0000, v54
	s_waitcnt vmcnt(9)
	v_max3_f32 v19, v66, v67, v68
	s_waitcnt vmcnt(8)
	v_lshlrev_b32_e32 v64, 16, v56
	v_and_b32_e32 v65, 0xffff0000, v56
	v_sub_f32_e32 v56, v66, v19
	v_sub_f32_e32 v66, v67, v19
	v_exp_f32_e32 v67, v56
	v_sub_f32_e32 v19, v68, v19
	v_exp_f32_e32 v68, v66
	v_exp_f32_e32 v19, v19
	v_add_f32_e32 v66, 0, v67
	v_lshlrev_b32_e32 v56, 16, v57
	v_add_f32_e32 v66, v68, v66
	v_add_f32_e32 v66, v19, v66
	v_div_scale_f32 v69, s[8:9], v66, v66, 1.0
	v_rcp_f32_e32 v70, v69
	v_div_scale_f32 v71, vcc, 1.0, v66, 1.0
	v_and_b32_e32 v57, 0xffff0000, v57
	v_fma_f32 v72, -v69, v70, 1.0
	v_fmac_f32_e32 v70, v72, v70
	v_mul_f32_e32 v72, v71, v70
	v_fma_f32 v73, -v69, v72, v71
	v_fmac_f32_e32 v72, v73, v70
	v_fma_f32 v69, -v69, v72, v71
	v_div_fmas_f32 v69, v69, v70, v72
	v_div_fixup_f32 v69, v69, v66, 1.0
	v_mul_f32_e32 v66, v67, v69
	v_mul_f32_e32 v68, v68, v69
	v_pk_fma_f32 v[64:65], v[66:67], v[64:65], 0 op_sel_hi:[0, 1, 0]
	v_pk_fma_f32 v[56:57], v[66:67], v[56:57], 0 op_sel_hi:[0, 1, 0]
	v_lshlrev_b32_e32 v54, 16, v55
	v_and_b32_e32 v55, 0xffff0000, v55
	v_mul_f32_e32 v70, v19, v69
	v_pk_fma_f32 v[60:61], v[68:69], v[60:61], v[64:65] op_sel_hi:[0, 1, 1]
	v_pk_fma_f32 v[52:53], v[68:69], v[52:53], v[56:57] op_sel_hi:[0, 1, 1]
	v_pk_fma_f32 v[56:57], v[70:71], v[62:63], v[60:61] op_sel_hi:[0, 1, 1]
	v_pk_fma_f32 v[52:53], v[70:71], v[54:55], v[52:53] op_sel_hi:[0, 1, 1]
	v_cvt_pk_bf16_f32 v54, v56, v57
	v_cvt_pk_bf16_f32 v55, v52, v53
	global_store_dwordx2 v[40:41], v[54:55], off offset:1536
	s_waitcnt vmcnt(8)
	v_mov_b32_e32 v64, v15
	s_waitcnt vmcnt(7)
	v_mov_b32_e32 v65, v7
	s_waitcnt vmcnt(6)
	v_mov_b32_e32 v72, v11
	s_waitcnt vmcnt(5)
	v_mov_b32_e32 v73, v3
	v_mov_b32_e32 v62, v14
	v_mov_b32_e32 v63, v6
	v_mov_b32_e32 v70, v10
	v_mov_b32_e32 v71, v2
	v_pk_mul_f32 v[64:65], v[64:65], v[64:65]
	v_pk_mul_f32 v[72:73], v[72:73], v[72:73]
	v_mov_b32_e32 v56, v16
	v_mov_b32_e32 v57, v8
	v_mov_b32_e32 v66, v12
	v_mov_b32_e32 v67, v4
	v_pk_fma_f32 v[62:63], v[62:63], v[62:63], v[64:65]
	v_pk_fma_f32 v[64:65], v[70:71], v[70:71], v[72:73]
	v_mov_b32_e32 v60, v17
	v_mov_b32_e32 v61, v9
	v_mov_b32_e32 v68, v13
	v_mov_b32_e32 v69, v5
	v_pk_fma_f32 v[56:57], v[56:57], v[56:57], v[62:63]
	v_pk_fma_f32 v[62:63], v[66:67], v[66:67], v[64:65]
	v_pk_fma_f32 v[56:57], v[60:61], v[60:61], v[56:57]
	v_pk_fma_f32 v[60:61], v[68:69], v[68:69], v[62:63]
	v_pk_add_f32 v[56:57], v[56:57], v[56:57] op_sel:[0, 1] op_sel_hi:[1, 0]
	s_waitcnt vmcnt(3)
; DI unsigned pack2(float a, float b) { f2_t v = {a, b}; return __builtin_bit_cast(unsigned, __builtin_convertvector(v, bf2_t)); }
; DI float siluf_(float x) { return x * __builtin_amdgcn_rcpf(1.f + __expf(-x)); }
; DI void phase_combine(CParams& p, int layer, const float* __restrict__ xg) {
;     ...
;       const u32x2 uf = ((const u32x2*)(OFb + (size_t)r * 256))[lane];
;       const u32x2 ub = ((const u32x2*)(OBb + (size_t)r * 256))[lane];
;       const u32x2 uz = ((const u32x2*)(PR + (size_t)r * NPR + C_Z))[lane];
;       float o[4], z[4];
;       o[0] = __uint_as_float(uf.x << 16) + __uint_as_float(ub.x << 16);
;       o[1] = __uint_as_float(uf.x & 0xffff0000u) + __uint_as_float(ub.x & 0xffff0000u);
;       o[2] = __uint_as_float(uf.y << 16) + __uint_as_float(ub.y << 16);
;       o[3] = __uint_as_float(uf.y & 0xffff0000u) + __uint_as_float(ub.y & 0xffff0000u);
;       z[0] = __uint_as_float(uz.x << 16); z[1] = __uint_as_float(uz.x & 0xffff0000u);
;       z[2] = __uint_as_float(uz.y << 16); z[3] = __uint_as_float(uz.y & 0xffff0000u);
;       float ss = o[0] * o[0] + o[1] * o[1] + o[2] * o[2] + o[3] * o[3];
;       ss += __shfl_xor(ss, 1); ss += __shfl_xor(ss, 2); ss += __shfl_xor(ss, 4); ss += __shfl_xor(ss, 8);
;       const float rs = rsqrtf(ss * (1.f / 64.f) + EPS);
;       const float4 gg = ((const float4*)gdn)[lane & 15];
;       u32x2 ou;
;       ou.x = pack2(o[0] * rs * gg.x * siluf_(z[0]), o[1] * rs * gg.y * siluf_(z[1]));
;       ou.y = pack2(o[2] * rs * gg.z * siluf_(z[2]), o[3] * rs * gg.w * siluf_(z[3]));
;       ((u32x2*)(Y + (size_t)r * 1024 + 512))[lane] = ou;
;     }
;     {
;       const float4* xr = (const float4*)(xg + (size_t)r * 1024);
;       float4 v[4];
;       float ss = 0.f;
; #pragma unroll
;       for (int i = 0; i < 4; ++i) { v[i] = xr[lane + 64 * i]; ss += v[i].x * v[i].x + v[i].y * v[i].y + v[i].z * v[i].z + v[i].w * v[i].w; }
;       ss = wave_sum(ss);
;       const float rs = rsqrtf(ss * (1.f / 1024.f) + EPS);
; #pragma unroll
;       for (int i = 0; i < 4; ++i) {
;         const float4 gg = ((const float4*)gmix)[lane + 64 * i];
;         u32x2 o; o.x = pack2(v[i].x * rs * gg.x, v[i].y * rs * gg.y); o.y = pack2(v[i].z * rs * gg.z, v[i].w * rs * gg.w);
;         ((u32x2*)(Np + (size_t)r * 1024))[lane + 64 * i] = o;
;       }
	v_lshlrev_b32_e32 v62, 16, v91
	v_and_b32_e32 v63, 0xffff0000, v91
	v_lshlrev_b32_e32 v64, 16, v90
	v_and_b32_e32 v65, 0xffff0000, v90
	s_waitcnt vmcnt(2)
	v_lshlrev_b32_e32 v52, 16, v92
	v_and_b32_e32 v53, 0xffff0000, v92
	v_pk_add_f32 v[52:53], v[64:65], v[52:53]
	v_pk_add_f32 v[56:57], v[56:57], v[60:61]
	v_pk_mul_f32 v[64:65], v[52:53], v[52:53]
	v_lshlrev_b32_e32 v60, 16, v93
	v_mov_b32_e32 v57, v64
	v_mov_b32_e32 v64, v61
	v_pk_add_f32 v[56:57], v[56:57], v[64:65]
	ds_bpermute_b32 v54, v50, v56
	v_and_b32_e32 v61, 0xffff0000, v93
	v_pk_add_f32 v[60:61], v[62:63], v[60:61]
	v_lshlrev_b32_e32 v64, 16, v58
	v_pk_mul_f32 v[62:63], v[60:61], v[60:61]
	v_and_b32_e32 v65, 0xffff0000, v58
	v_mov_b32_e32 v55, v62
	s_waitcnt lgkmcnt(0)
	v_pk_add_f32 v[54:55], v[56:57], v[54:55]
	ds_bpermute_b32 v62, v51, v54
	v_lshlrev_b32_e32 v56, 16, v59
	v_and_b32_e32 v57, 0xffff0000, v59
	v_mul_f32_e32 v19, 0xbfb8aa3b, v64
	v_exp_f32_e32 v19, v19
	s_waitcnt lgkmcnt(0)
	v_pk_add_f32 v[54:55], v[54:55], v[62:63]
	ds_bpermute_b32 v59, v46, v55
	ds_bpermute_b32 v58, v49, v54
	v_mul_f32_e32 v62, 0xbfb8aa3b, v65
	v_exp_f32_e32 v62, v62
	v_mul_f32_e32 v63, 0xbfb8aa3b, v56
	v_mul_f32_e32 v66, 0xbfb8aa3b, v57
	s_waitcnt lgkmcnt(0)
	v_pk_add_f32 v[54:55], v[54:55], v[58:59]
	ds_bpermute_b32 v59, v47, v55
	ds_bpermute_b32 v58, v48, v54
	v_exp_f32_e32 v63, v63
	v_add_f32_e32 v19, 1.0, v19
	v_exp_f32_e32 v66, v66
	v_add_f32_e32 v67, 1.0, v62
	s_waitcnt lgkmcnt(0)
	v_pk_add_f32 v[54:55], v[54:55], v[58:59]
	ds_bpermute_b32 v59, v48, v55
	ds_bpermute_b32 v58, v47, v54
	v_rcp_f32_e32 v62, v19
	v_add_f32_e32 v68, 1.0, v63
	v_rcp_f32_e32 v63, v67
	v_add_f32_e32 v69, 1.0, v66
	s_waitcnt lgkmcnt(0)
	v_pk_add_f32 v[54:55], v[54:55], v[58:59]
	ds_bpermute_b32 v59, v49, v55
	ds_bpermute_b32 v58, v46, v54
	v_rcp_f32_e32 v66, v68
	v_rcp_f32_e32 v67, v69
	s_waitcnt lgkmcnt(0)
	v_pk_add_f32 v[54:55], v[54:55], v[58:59]
	s_nop 0
	v_pk_fma_f32 v[54:55], v[54:55], s[38:39], v[216:217] op_sel_hi:[1, 1, 0]
	v_pk_mul_f32 v[58:59], v[62:63], v[64:65]
	v_mul_f32_e32 v19, 0x4b800000, v55
	v_cmp_gt_f32_e32 vcc, s15, v55
	v_pk_mul_f32 v[56:57], v[66:67], v[56:57]
	s_nop 0
	v_cndmask_b32_e32 v19, v55, v19, vcc
	v_rsq_f32_e32 v19, v19
	s_nop 0
	v_mul_f32_e32 v55, 0x45800000, v19
	v_cndmask_b32_e32 v62, v19, v55, vcc
	v_pk_mul_f32 v[52:53], v[52:53], v[62:63] op_sel_hi:[1, 0]
	v_pk_mul_f32 v[60:61], v[60:61], v[62:63] op_sel_hi:[1, 0]
	s_waitcnt vmcnt(1)
	v_pk_mul_f32 v[42:43], v[94:95], v[52:53]
	v_pk_mul_f32 v[44:45], v[96:97], v[60:61]
	v_pk_mul_f32 v[42:43], v[58:59], v[42:43]
	v_pk_mul_f32 v[44:45], v[56:57], v[44:45]
	v_cvt_pk_bf16_f32 v42, v42, v43
	v_cvt_pk_bf16_f32 v43, v44, v45
	global_store_dwordx2 v[40:41], v[42:43], off offset:1024
	v_mul_f32_e32 v19, 0x4b800000, v54
	v_cmp_gt_f32_e32 vcc, s15, v54
	s_nop 1
	v_cndmask_b32_e32 v19, v54, v19, vcc
	v_rsq_f32_e32 v19, v19
	s_nop 0
	v_mul_f32_e32 v44, 0x45800000, v19
	v_cndmask_b32_e32 v44, v19, v44, vcc
	v_pk_mul_f32 v[14:15], v[14:15], v[44:45] op_sel_hi:[1, 0]
	v_pk_mul_f32 v[16:17], v[16:17], v[44:45] op_sel_hi:[1, 0]
	v_pk_mul_f32 v[6:7], v[6:7], v[44:45] op_sel_hi:[1, 0]
	v_pk_mul_f32 v[8:9], v[8:9], v[44:45] op_sel_hi:[1, 0]
	v_pk_mul_f32 v[10:11], v[10:11], v[44:45] op_sel_hi:[1, 0]
	v_pk_mul_f32 v[12:13], v[12:13], v[44:45] op_sel_hi:[1, 0]
	v_pk_mul_f32 v[2:3], v[2:3], v[44:45] op_sel_hi:[1, 0]
	v_pk_mul_f32 v[4:5], v[4:5], v[44:45] op_sel_hi:[1, 0]
	v_cmp_lt_i32_e32 vcc, s28, v18
	s_or_b64 s[6:7], vcc, s[6:7]
	v_pk_mul_f32 v[14:15], v[74:75], v[14:15]
	v_pk_mul_f32 v[16:17], v[76:77], v[16:17]
	v_cvt_pk_bf16_f32 v14, v14, v15
	v_cvt_pk_bf16_f32 v15, v16, v17
	global_store_dwordx2 v[38:39], v[14:15], off
	v_pk_mul_f32 v[6:7], v[78:79], v[6:7]
	v_pk_mul_f32 v[8:9], v[80:81], v[8:9]
	v_cvt_pk_bf16_f32 v6, v6, v7
	v_cvt_pk_bf16_f32 v7, v8, v9
	global_store_dwordx2 v[38:39], v[6:7], off offset:512
	v_pk_mul_f32 v[6:7], v[82:83], v[10:11]
	v_pk_mul_f32 v[8:9], v[12:13], v[84:85]
	v_cvt_pk_bf16_f32 v6, v6, v7
	v_cvt_pk_bf16_f32 v7, v8, v9
	global_store_dwordx2 v[38:39], v[6:7], off offset:1024
	v_pk_mul_f32 v[2:3], v[2:3], v[86:87]
	v_pk_mul_f32 v[4:5], v[4:5], v[88:89]
	v_cvt_pk_bf16_f32 v2, v2, v3
	v_cvt_pk_bf16_f32 v3, v4, v5
	global_store_dwordx2 v[38:39], v[2:3], off offset:1536
	s_andn2_b64 exec, exec, s[6:7]
	s_cbranch_execnz .LBB0_907
